# v61: phase-2 attention-block and scan units indexed XCD-locally (unit = (blockIdx%8)*32 + blockIdx/8) so each XCD consumes the IN outputs it produced and produces the GLU/ATT inputs it will consume
# speedup vs baseline: 1.0116x; 1.0070x over previous
; __device__ __forceinline__ void attn_block_unit(const Params& p, int bu, char* lds, int tid) {
;   const int b = bu >> 5, kv = (bu >> 4) & 1, blk = bu & 15, lane = tid & 63, wid = tid >> 6;
;   const bf16_t* Kp = (const bf16_t*)(p.ws + OFF_KP); const bf16_t* Vtp = (const bf16_t*)(p.ws + OFF_VTP);
;   char* K_l = lds; char* Vt_l = lds + ATT_VOFF;
;   u32x4 kr[4], vr[4];
; #pragma unroll
;   for (int i = 0; i < 4; ++i) {
;     const int piece = tid + i * NTHR, key = piece >> 3, c = piece & 7;
;     if (blk > 0 || key >= 128) kr[i] = *(const u32x4*)(Kp + ((size_t)b * 2048 + (size_t)(blk - 1) * 128 + key) * 128 + kv * 64 + c * 8);
;     const int d = piece >> 5, c2 = piece & 31;
;     if (blk > 0 || c2 >= 16) vr[i] = *(const u32x4*)(Vtp + ((size_t)(b * 2 + kv) * 64 + d) * 2048 + (size_t)(blk - 1) * 128 + c2 * 8);
;   }
; #pragma unroll
;   for (int i = 0; i < 4; ++i) {
;     const int piece = tid + i * NTHR, key = piece >> 3, c = piece & 7;
;     if (blk > 0 || key >= 128) *(u32x4*)(K_l + key * ATT_KSTR + c * 16) = kr[i];
;     const int d = piece >> 5, c2 = piece & 31;
;     if (blk > 0 || c2 >= 16) *(u32x4*)(Vt_l + d * ATT_VSTR + c2 * 16) = vr[i];
;   }
;   __syncthreads();
;   const int pl = lane & 15;
; #pragma unroll 1
;   for (int g = 0; g < 4; ++g) {
;     asm volatile("" ::: "memory");
;     attn_core<true>(p, lane, K_l, ATT_KSTR, Vt_l, ATT_VSTR, wid, blk > 0, b * 2048 + blk * 128 + wid * 16 + pl, kv * 4 + g, wid * 16 + pl);
; __global__ void __launch_bounds__(512) fwd_megakernel(Params p) {
;     ...
;     for (int bu = blockIdx.x; bu < 256; bu += gridDim.x) attn_block_unit(p, bu, lds, threadIdx.x);
.LBB0_500:
	s_or_b64 exec, exec, s[0:1]
	v_readlane_b32 s0, v244, 33
	s_cmpk_lt_i32 s0, 0x100
	s_cselect_b64 s[4:5], -1, 0
	v_writelane_b32 v244, s4, 60
	s_cmpk_gt_i32 s0, 0xff
	s_cselect_b64 s[0:1], -1, 0
	v_writelane_b32 v244, s5, 61
	v_writelane_b32 v244, s0, 62
	s_and_b64 vcc, exec, s[0:1]
	v_and_b32_e32 v78, 15, v0
	v_lshrrev_b32_e32 v79, 4, v184
	v_and_b32_e32 v82, 48, v0
	v_or_b32_e32 v80, 48, v184
	v_mbcnt_lo_u32_b32 v185, -1, 0
	s_waitcnt lgkmcnt(0)
	s_barrier
	v_writelane_b32 v244, s1, 63
	s_cbranch_vccnz .LBB0_529
	v_readlane_b32 s8, v244, 0
	v_lshlrev_b32_e32 v2, 4, v0
	v_mov_b32_e32 v6, 0
	v_readlane_b32 s10, v244, 2
	v_readlane_b32 s11, v244, 3
	v_and_b32_e32 v2, 0x70, v2
	v_mov_b32_e32 v3, v6
	v_lshl_add_u64 v[4:5], s[10:11], 0, v[2:3]
	v_lshlrev_b32_e32 v3, 6, v0
	s_mov_b64 s[4:5], 0xa500000
	v_and_b32_e32 v8, 0x7800, v3
	v_or_b32_e32 v3, 0x200, v0
	v_lshl_add_u64 v[84:85], v[4:5], 0, s[4:5]
	v_lshlrev_b32_e32 v5, 6, v3
	v_and_b32_e32 v10, 0xf800, v5
	v_or_b32_e32 v5, 0x400, v0
	v_lshlrev_b32_e32 v7, 6, v5
	v_lshlrev_b32_e32 v20, 4, v183
	v_add_u32_e32 v113, 1, v183
	v_lshlrev_b32_e32 v24, 2, v79
	v_and_b32_e32 v12, 0x17800, v7
	v_or_b32_e32 v7, 0x600, v0
	v_or_b32_e32 v81, v20, v78
	v_add_u32_e32 v115, 2, v183
	v_or_b32_e32 v128, v24, v20
	v_bitop3_b32 v129, v24, v20, v24 bitop3:3
	v_lshlrev_b32_e32 v20, 4, v113
	v_lshlrev_b32_e32 v9, 6, v7
	v_add_u32_e32 v117, 3, v183
	v_or_b32_e32 v130, v24, v20
	v_bitop3_b32 v131, v24, v20, v24 bitop3:3
	v_lshlrev_b32_e32 v20, 4, v115
	v_and_b32_e32 v14, 0x1f800, v9
	v_add_u32_e32 v9, 0, v2
	v_lshrrev_b32_e32 v2, 5, v0
	v_add_u32_e32 v119, 4, v183
	v_or_b32_e32 v132, v24, v20
	v_bitop3_b32 v133, v24, v20, v24 bitop3:3
	v_lshlrev_b32_e32 v20, 4, v117
	v_cmp_lt_u32_e64 s[0:1], 15, v135
	v_lshlrev_b32_e32 v4, 3, v135
	v_lshl_add_u32 v11, v135, 4, 0
	v_mul_u32_u24_e32 v15, 0x210, v2
	v_lshrrev_b32_e32 v2, 5, v3
	v_add_u32_e32 v121, 5, v183
	v_or_b32_e32 v135, v24, v20
	v_bitop3_b32 v136, v24, v20, v24 bitop3:3
	v_lshlrev_b32_e32 v20, 4, v119
	v_mul_u32_u24_e32 v18, 0x210, v2
	v_lshrrev_b32_e32 v2, 5, v5
	v_add_u32_e32 v123, 6, v183
	v_or_b32_e32 v137, v24, v20
	v_bitop3_b32 v138, v24, v20, v24 bitop3:3
	v_lshlrev_b32_e32 v20, 4, v121
	v_lshrrev_b32_e32 v88, 3, v5
	v_mul_u32_u24_e32 v5, 0x210, v2
	v_lshrrev_b32_e32 v2, 5, v7
	v_add_u32_e32 v125, 7, v183
	v_or_b32_e32 v21, 8, v183
	v_or_b32_e32 v139, v24, v20
	v_bitop3_b32 v140, v24, v20, v24 bitop3:3
	v_lshlrev_b32_e32 v20, 4, v123
	v_lshrrev_b32_e32 v90, 3, v7
	v_mul_u32_u24_e32 v7, 0x210, v2
	v_lshlrev_b32_e32 v2, 3, v79
	v_lshlrev_b32_e32 v22, 4, v21
	v_or_b32_e32 v141, v24, v20
	v_bitop3_b32 v142, v24, v20, v24 bitop3:3
	v_lshlrev_b32_e32 v20, 4, v125
	v_lshrrev_b32_e32 v86, 3, v3
	s_movk_i32 s6, 0x210
	v_mov_b32_e32 v3, v6
	v_or_b32_e32 v23, v22, v78
	v_or_b32_e32 v143, v24, v20
	v_bitop3_b32 v144, v24, v20, v24 bitop3:3
	v_add_u32_e32 v20, 0, v2
	s_add_u32 s3, s10, 0xa900000
	s_movk_i32 s4, 0x1ff
	v_mul_u32_u24_e32 v13, 0x90, v134
	v_mul_u32_u24_e32 v16, 0x90, v86
	v_mul_u32_u24_e32 v17, 0x90, v88
	v_mul_u32_u24_e32 v19, 0x90, v90
	v_add_u32_e32 v112, 0, v82
	v_mul_u32_u24_e32 v23, 0x90, v23
	v_mad_u32_u24 v147, v78, s6, v20
	v_mad_u32_u24 v148, v80, s6, v20
	v_mov_b32_e32 v83, v6
	v_lshl_add_u64 v[2:3], s[10:11], 0, v[2:3]
	s_mov_b64 s[6:7], 0x7380040
	v_readlane_b32 s83, v244, 33
	s_addc_u32 s81, s11, 0
	s_nop 3
	s_cmp_lg_u32 s33, 0x100
	s_cbranch_scc1 .Lp2mapa
	s_and_b32 s98, s83, 7
	s_lshl_b32 s98, s98, 5
	s_lshr_b32 s99, s83, 3
	s_or_b32 s83, s98, s99
.Lp2mapa:
	v_cmp_lt_u32_e64 s[4:5], s4, v0
	v_mov_b32_e32 v87, v6
	v_mov_b32_e32 v89, v6
	v_mov_b32_e32 v91, v6
	s_mov_b32 s85, 0
	v_max_u32_e32 v114, 8, v113
	v_max_u32_e32 v116, 8, v115
	v_max_u32_e32 v118, 8, v117
	v_max_u32_e32 v120, 8, v119
	v_max_u32_e32 v122, 8, v121
	v_max_u32_e32 v124, 8, v123
	v_max_u32_e32 v126, 8, v125
	v_mov_b32_e32 v127, 0x7f
	v_or_b32_e32 v145, v24, v22
	v_bitop3_b32 v146, v24, v22, v24 bitop3:3
	v_lshlrev_b32_e32 v149, 5, v21
	v_lshl_add_u64 v[92:93], s[10:11], 0, v[82:83]
	v_lshl_add_u64 v[94:95], v[2:3], 0, s[6:7]
	v_lshlrev_b32_e32 v96, 1, v4
	v_lshlrev_b32_e32 v98, 1, v8
	v_lshlrev_b32_e32 v100, 1, v10
	v_lshlrev_b32_e32 v102, 1, v12
	v_lshlrev_b32_e32 v104, 1, v14
	v_add_u32_e32 v83, v9, v13
	v_add_u32_e32 v150, v11, v15
	v_add_u32_e32 v151, v9, v16
	v_add_u32_e32 v152, v11, v18
	v_add_u32_e32 v153, v11, v5
	v_add_u32_e32 v154, v9, v19
	v_add_u32_e32 v155, v11, v7
	v_add_u32_e32 v156, v112, v23
	v_add_u32_e32 v157, v9, v17
	v_mov_b32_e32 v158, 0xff800000
	v_mbcnt_hi_u32_b32 v159, -1, v185
	s_mov_b32 s82, s83
	v_readlane_b32 s9, v244, 1

; __device__ __forceinline__ void scan_end_unit(const Params& p, int u, int lane) {
;   unsigned char* ws = p.ws;
;   const int pl = lane & 15, q4 = lane >> 4;
;   const bf16_t* P = (const bf16_t*)(ws + OFF_P);
;   const float* AR = (const float*)(ws + OFF_AR); const float* AI = (const float*)(ws + OFF_AI);
;   const bf16_t* BB = (const bf16_t*)(ws + OFF_BB);
;   float* E = (float*)(ws + OFF_E);
;   const int c = u & 15, g = (u >> 4) & 31, s = u >> 9, R0 = s * 2048 + c * 128;
;   float ar[4], ai[4], wr_[4], wi_[4], a16r[4], a16i[4];
; #pragma unroll
;   for (int q = 0; q < 4; ++q) {
;     const float r1 = AR[g * 64 + q * 16 + pl], i1 = AI[g * 64 + q * 16 + pl];
;     ar[q] = r1; ai[q] = i1;
;     const float r2 = r1 * r1 - i1 * i1, i2 = 2.f * r1 * i1;
;     const float r4 = r2 * r2 - i2 * i2, i4 = 2.f * r2 * i2;
;     const float r8 = r4 * r4 - i4 * i4, i8 = 2.f * r4 * i4;
;     const float r12 = r8 * r4 - i8 * i4, i12 = r8 * i4 + i8 * r4;
;     a16r[q] = r8 * r8 - i8 * i8; a16i[q] = 2.f * r8 * i8;
;     wr_[q] = (q4 == 0) ? r12 : (q4 == 1) ? r8 : (q4 == 2) ? r4 : 1.f;
;     wi_[q] = (q4 == 0) ? i12 : (q4 == 1) ? i8 : (q4 == 2) ? i4 : 0.f;
;   }
;   bf16x4 bb[8];
; #pragma unroll
;   for (int pt = 0; pt < 8; ++pt) bb[pt] = *(const bf16x4*)(BB + ((size_t)g * 128 + pt * 16 + pl) * 16 + q4 * 4);
;   float er[4], ei[4];
; #pragma unroll
;   for (int q = 0; q < 4; ++q) { er[q] = 0.f; ei[q] = 0.f; }
;   const bf16_t* up = P + (size_t)(R0 + pl) * PW + g * 16 + q4 * 4;
;   bf16x4 uf_next = *(const bf16x4*)up;
; __global__ void __launch_bounds__(512) fwd_megakernel(Params p) {
;     ...
;     for (int u = blockIdx.x * 16 + wid; u < 4096; u += ((u & 15) + NWAVE < 15) ? NWAVE : (gridDim.x * 16 - (u & 15) + wid)) {
;       asm volatile("" ::: "memory");
;       scan_end_unit(p, u, lane);
.LBB0_529:
	v_readlane_b32 s4, v244, 0
	v_readlane_b32 s6, v244, 2
	v_readlane_b32 s7, v244, 3
	s_add_u32 s22, s6, 0xe200000
	s_addc_u32 s23, s7, 0
	s_add_u32 s24, s6, 0xe202000
	v_readlane_b32 s0, v244, 33
	s_addc_u32 s25, s7, 0
	s_nop 3
	s_cmp_lg_u32 s33, 0x100
	s_cbranch_scc1 .Lp2mapb
	s_and_b32 s98, s0, 7
	s_lshl_b32 s98, s98, 5
	s_lshr_b32 s99, s0, 3
	s_or_b32 s0, s98, s99
.Lp2mapb:
	s_lshl_b32 s3, s0, 4
	v_or_b32_e32 v187, s3, v183
	s_movk_i32 s0, 0x1000
	v_cmp_gt_i32_e64 s[0:1], s0, v187
	v_lshl_or_b32 v224, s33, 4, v183
	v_readlane_b32 s5, v244, 1
	s_and_saveexec_b64 s[10:11], s[0:1]
	v_readlane_b32 s66, v244, 51
	v_readlane_b32 s67, v244, 52
	s_cbranch_execz .LBB0_538
	v_readlane_b32 s12, v244, 57
	v_mov_b32_e32 v3, 0
	v_lshlrev_b32_e32 v2, 3, v79
	v_readlane_b32 s13, v244, 58
	v_readlane_b32 s28, v244, 0
	v_readlane_b32 s30, v244, 2
	v_lshl_add_u64 v[4:5], s[12:13], 0, v[2:3]
	v_lshlrev_b32_e32 v2, 4, v78
	v_mbcnt_hi_u32_b32 v90, -1, v185
	v_lshlrev_b32_e32 v8, 2, v79
	v_readlane_b32 s31, v244, 3
	s_add_u32 s12, s30, 0xe224000
	v_lshlrev_b32_e32 v83, 1, v2
	v_and_b32_e32 v2, 64, v90
	v_cmp_gt_u32_e64 s[4:5], 16, v184
	v_cmp_eq_u32_e64 s[6:7], 1, v79
	v_cmp_eq_u32_e64 s[8:9], 2, v79
	s_addc_u32 s13, s31, 0
	s_mov_b64 s[14:15], 0
	v_lshlrev_b32_e32 v81, 2, v78
	s_movk_i32 s18, 0x1800
	v_mov_b64_e32 v[6:7], s[30:31]
	v_lshlrev_b32_e32 v8, 1, v8
	v_mov_b32_e32 v9, v3
	v_xor_b32_e32 v91, 16, v90
	v_add_u32_e32 v92, 64, v2
	v_xor_b32_e32 v93, 32, v90
	v_lshlrev_b32_e32 v10, 2, v184
	s_movk_i32 s19, 0xfff
	v_mov_b32_e32 v94, v187
	v_readlane_b32 s29, v244, 1
	s_branch .LBB0_532
